# LoRA-input rows: 18 masked loads per row issued up front; init silu(c) table: 36 loads up front; conversion loops as previous
# baseline (speedup 1.0000x reference)
; __device__ __forceinline__ float fsilu(float x) { return x * __builtin_amdgcn_rcpf(1.0f + fexp(-x)); }
; __device__ __forceinline__ void phase_init(const Frame& F, ArgsRef A) {
;     ...
;     for (int i = F.tid; i < 9 * 2048; i += NTHR) { const int bs = i >> 11, k = i & 2047; const float v = bs < 8 ? c[bs * 2048 + k] : cctx[k]; sc[i] = fsilu(v); }
;     __syncthreads();
.LBB0_11:
	s_mov_b64 s[12:13], 0x1000
	global_load_dword v10, v[2:3], off
	global_load_dword v11, v[2:3], off offset:2048
	v_lshl_add_u64 v[2:3], v[2:3], 0, s[12:13]
	global_load_dword v12, v[2:3], off
	global_load_dword v13, v[2:3], off offset:2048
	v_lshl_add_u64 v[2:3], v[2:3], 0, s[12:13]
	global_load_dword v14, v[2:3], off
	global_load_dword v15, v[2:3], off offset:2048
	v_lshl_add_u64 v[2:3], v[2:3], 0, s[12:13]
	global_load_dword v16, v[2:3], off
	global_load_dword v17, v[2:3], off offset:2048
	v_lshl_add_u64 v[2:3], v[2:3], 0, s[12:13]
	global_load_dword v18, v[2:3], off
	global_load_dword v19, v[2:3], off offset:2048
	v_lshl_add_u64 v[2:3], v[2:3], 0, s[12:13]
	global_load_dword v20, v[2:3], off
	global_load_dword v21, v[2:3], off offset:2048
	v_lshl_add_u64 v[2:3], v[2:3], 0, s[12:13]
	global_load_dword v22, v[2:3], off
	global_load_dword v23, v[2:3], off offset:2048
	v_lshl_add_u64 v[2:3], v[2:3], 0, s[12:13]
	global_load_dword v24, v[2:3], off
	global_load_dword v25, v[2:3], off offset:2048
	v_lshl_add_u64 v[2:3], v[2:3], 0, s[12:13]
	global_load_dword v26, v[2:3], off
	global_load_dword v27, v[2:3], off offset:2048
	v_lshl_add_u64 v[2:3], v[2:3], 0, s[12:13]
	global_load_dword v28, v[2:3], off
	global_load_dword v29, v[2:3], off offset:2048
	v_lshl_add_u64 v[2:3], v[2:3], 0, s[12:13]
	global_load_dword v30, v[2:3], off
	global_load_dword v31, v[2:3], off offset:2048
	v_lshl_add_u64 v[2:3], v[2:3], 0, s[12:13]
	global_load_dword v32, v[2:3], off
	global_load_dword v33, v[2:3], off offset:2048
	v_lshl_add_u64 v[2:3], v[2:3], 0, s[12:13]
	global_load_dword v34, v[2:3], off
	global_load_dword v35, v[2:3], off offset:2048
	v_lshl_add_u64 v[2:3], v[2:3], 0, s[12:13]
	global_load_dword v36, v[2:3], off
	global_load_dword v37, v[2:3], off offset:2048
	v_lshl_add_u64 v[2:3], v[2:3], 0, s[12:13]
	global_load_dword v38, v[2:3], off
	global_load_dword v39, v[2:3], off offset:2048
	v_lshl_add_u64 v[2:3], v[2:3], 0, s[12:13]
	global_load_dword v40, v[2:3], off
	global_load_dword v41, v[2:3], off offset:2048
	v_lshlrev_b32_e32 v4, 2, v0
	v_lshl_add_u64 v[8:9], s[4:5], 0, v[4:5]
	global_load_dword v42, v[8:9], off
	global_load_dword v43, v[8:9], off offset:2048
	v_lshl_add_u64 v[8:9], v[8:9], 0, s[12:13]
	global_load_dword v44, v[8:9], off
	global_load_dword v45, v[8:9], off offset:2048
	s_waitcnt vmcnt(35)
	v_mul_f32_e32 v9, 0xbfb8aa3b, v10
	v_exp_f32_e32 v9, v9
	s_nop 0
	v_add_f32_e32 v1, 1.0, v9
	v_rcp_f32_e32 v9, v1
	s_nop 0
	v_mul_f32_e32 v10, v10, v9
	ds_write_b32 v7, v10
	s_waitcnt vmcnt(34)
	v_mul_f32_e32 v9, 0xbfb8aa3b, v11
	v_exp_f32_e32 v9, v9
	s_nop 0
	v_add_f32_e32 v1, 1.0, v9
	v_rcp_f32_e32 v9, v1
	s_nop 0
	v_mul_f32_e32 v11, v11, v9
	ds_write_b32 v7, v11 offset:2048
	s_waitcnt vmcnt(33)
	v_mul_f32_e32 v9, 0xbfb8aa3b, v12
	v_exp_f32_e32 v9, v9
	s_nop 0
	v_add_f32_e32 v1, 1.0, v9
	v_rcp_f32_e32 v9, v1
	s_nop 0
	v_mul_f32_e32 v12, v12, v9
	ds_write_b32 v7, v12 offset:4096
	s_waitcnt vmcnt(32)
	v_mul_f32_e32 v9, 0xbfb8aa3b, v13
	v_exp_f32_e32 v9, v9
	s_nop 0
	v_add_f32_e32 v1, 1.0, v9
	v_rcp_f32_e32 v9, v1
	s_nop 0
	v_mul_f32_e32 v13, v13, v9
	ds_write_b32 v7, v13 offset:6144
	s_waitcnt vmcnt(31)
	v_mul_f32_e32 v9, 0xbfb8aa3b, v14
	v_exp_f32_e32 v9, v9
	s_nop 0
	v_add_f32_e32 v1, 1.0, v9
	v_rcp_f32_e32 v9, v1
	s_nop 0
	v_mul_f32_e32 v14, v14, v9
	ds_write_b32 v7, v14 offset:8192
	s_waitcnt vmcnt(30)
	v_mul_f32_e32 v9, 0xbfb8aa3b, v15
	v_exp_f32_e32 v9, v9
	s_nop 0
	v_add_f32_e32 v1, 1.0, v9
	v_rcp_f32_e32 v9, v1
	s_nop 0
	v_mul_f32_e32 v15, v15, v9
	ds_write_b32 v7, v15 offset:10240
	s_waitcnt vmcnt(29)
	v_mul_f32_e32 v9, 0xbfb8aa3b, v16
	v_exp_f32_e32 v9, v9
	s_nop 0
	v_add_f32_e32 v1, 1.0, v9
	v_rcp_f32_e32 v9, v1
	s_nop 0
	v_mul_f32_e32 v16, v16, v9
	ds_write_b32 v7, v16 offset:12288
	s_waitcnt vmcnt(28)
	v_mul_f32_e32 v9, 0xbfb8aa3b, v17
	v_exp_f32_e32 v9, v9
	s_nop 0
	v_add_f32_e32 v1, 1.0, v9
	v_rcp_f32_e32 v9, v1
	s_nop 0
	v_mul_f32_e32 v17, v17, v9
	ds_write_b32 v7, v17 offset:14336
	s_waitcnt vmcnt(27)
	v_mul_f32_e32 v9, 0xbfb8aa3b, v18
	v_exp_f32_e32 v9, v9
	s_nop 0
	v_add_f32_e32 v1, 1.0, v9
	v_rcp_f32_e32 v9, v1
	s_nop 0
	v_mul_f32_e32 v18, v18, v9
	ds_write_b32 v7, v18 offset:16384
	s_waitcnt vmcnt(26)
	v_mul_f32_e32 v9, 0xbfb8aa3b, v19
	v_exp_f32_e32 v9, v9
	s_nop 0
	v_add_f32_e32 v1, 1.0, v9
	v_rcp_f32_e32 v9, v1
	s_nop 0
	v_mul_f32_e32 v19, v19, v9
	ds_write_b32 v7, v19 offset:18432
	s_waitcnt vmcnt(25)
	v_mul_f32_e32 v9, 0xbfb8aa3b, v20
	v_exp_f32_e32 v9, v9
	s_nop 0
	v_add_f32_e32 v1, 1.0, v9
	v_rcp_f32_e32 v9, v1
	s_nop 0
	v_mul_f32_e32 v20, v20, v9
	ds_write_b32 v7, v20 offset:20480
	s_waitcnt vmcnt(24)
	v_mul_f32_e32 v9, 0xbfb8aa3b, v21
	v_exp_f32_e32 v9, v9
	s_nop 0
	v_add_f32_e32 v1, 1.0, v9
	v_rcp_f32_e32 v9, v1
	s_nop 0
	v_mul_f32_e32 v21, v21, v9
	ds_write_b32 v7, v21 offset:22528
	s_waitcnt vmcnt(23)
; __device__ __forceinline__ float fsilu(float x) { return x * __builtin_amdgcn_rcpf(1.0f + fexp(-x)); }
; __device__ __forceinline__ void phase_init(const Frame& F, ArgsRef A) {
;     ...
;     for (int i = F.tid; i < 9 * 2048; i += NTHR) { const int bs = i >> 11, k = i & 2047; const float v = bs < 8 ? c[bs * 2048 + k] : cctx[k]; sc[i] = fsilu(v); }
;     __syncthreads();
	v_mul_f32_e32 v9, 0xbfb8aa3b, v22
	v_exp_f32_e32 v9, v9
	s_nop 0
	v_add_f32_e32 v1, 1.0, v9
	v_rcp_f32_e32 v9, v1
	s_nop 0
	v_mul_f32_e32 v22, v22, v9
	ds_write_b32 v7, v22 offset:24576
	s_waitcnt vmcnt(22)
	v_mul_f32_e32 v9, 0xbfb8aa3b, v23
	v_exp_f32_e32 v9, v9
	s_nop 0
	v_add_f32_e32 v1, 1.0, v9
	v_rcp_f32_e32 v9, v1
	s_nop 0
	v_mul_f32_e32 v23, v23, v9
	ds_write_b32 v7, v23 offset:26624
	s_waitcnt vmcnt(21)
	v_mul_f32_e32 v9, 0xbfb8aa3b, v24
	v_exp_f32_e32 v9, v9
	s_nop 0
	v_add_f32_e32 v1, 1.0, v9
	v_rcp_f32_e32 v9, v1
	s_nop 0
	v_mul_f32_e32 v24, v24, v9
	ds_write_b32 v7, v24 offset:28672
	s_waitcnt vmcnt(20)
	v_mul_f32_e32 v9, 0xbfb8aa3b, v25
	v_exp_f32_e32 v9, v9
	s_nop 0
	v_add_f32_e32 v1, 1.0, v9
	v_rcp_f32_e32 v9, v1
	s_nop 0
	v_mul_f32_e32 v25, v25, v9
	ds_write_b32 v7, v25 offset:30720
	s_waitcnt vmcnt(19)
	v_mul_f32_e32 v9, 0xbfb8aa3b, v26
	v_exp_f32_e32 v9, v9
	s_nop 0
	v_add_f32_e32 v1, 1.0, v9
	v_rcp_f32_e32 v9, v1
	s_nop 0
	v_mul_f32_e32 v26, v26, v9
	ds_write_b32 v7, v26 offset:32768
	s_waitcnt vmcnt(18)
	v_mul_f32_e32 v9, 0xbfb8aa3b, v27
	v_exp_f32_e32 v9, v9
	s_nop 0
	v_add_f32_e32 v1, 1.0, v9
	v_rcp_f32_e32 v9, v1
	s_nop 0
	v_mul_f32_e32 v27, v27, v9
	ds_write_b32 v7, v27 offset:34816
	s_waitcnt vmcnt(17)
	v_mul_f32_e32 v9, 0xbfb8aa3b, v28
	v_exp_f32_e32 v9, v9
	s_nop 0
	v_add_f32_e32 v1, 1.0, v9
	v_rcp_f32_e32 v9, v1
	s_nop 0
	v_mul_f32_e32 v28, v28, v9
	ds_write_b32 v7, v28 offset:36864
	s_waitcnt vmcnt(16)
	v_mul_f32_e32 v9, 0xbfb8aa3b, v29
	v_exp_f32_e32 v9, v9
	s_nop 0
	v_add_f32_e32 v1, 1.0, v9
	v_rcp_f32_e32 v9, v1
	s_nop 0
	v_mul_f32_e32 v29, v29, v9
	ds_write_b32 v7, v29 offset:38912
	s_waitcnt vmcnt(15)
	v_mul_f32_e32 v9, 0xbfb8aa3b, v30
	v_exp_f32_e32 v9, v9
	s_nop 0
	v_add_f32_e32 v1, 1.0, v9
	v_rcp_f32_e32 v9, v1
	s_nop 0
	v_mul_f32_e32 v30, v30, v9
	ds_write_b32 v7, v30 offset:40960
	s_waitcnt vmcnt(14)
	v_mul_f32_e32 v9, 0xbfb8aa3b, v31
	v_exp_f32_e32 v9, v9
	s_nop 0
	v_add_f32_e32 v1, 1.0, v9
	v_rcp_f32_e32 v9, v1
	s_nop 0
	v_mul_f32_e32 v31, v31, v9
	ds_write_b32 v7, v31 offset:43008
	s_waitcnt vmcnt(13)
	v_mul_f32_e32 v9, 0xbfb8aa3b, v32
	v_exp_f32_e32 v9, v9
	s_nop 0
	v_add_f32_e32 v1, 1.0, v9
	v_rcp_f32_e32 v9, v1
	s_nop 0
	v_mul_f32_e32 v32, v32, v9
	ds_write_b32 v7, v32 offset:45056
	s_waitcnt vmcnt(12)
	v_mul_f32_e32 v9, 0xbfb8aa3b, v33
	v_exp_f32_e32 v9, v9
	s_nop 0
	v_add_f32_e32 v1, 1.0, v9
	v_rcp_f32_e32 v9, v1
	s_nop 0
	v_mul_f32_e32 v33, v33, v9
	ds_write_b32 v7, v33 offset:47104
	s_waitcnt vmcnt(11)
	v_mul_f32_e32 v9, 0xbfb8aa3b, v34
	v_exp_f32_e32 v9, v9
	s_nop 0
	v_add_f32_e32 v1, 1.0, v9
	v_rcp_f32_e32 v9, v1
	s_nop 0
	v_mul_f32_e32 v34, v34, v9
	ds_write_b32 v7, v34 offset:49152
	s_waitcnt vmcnt(10)
	v_mul_f32_e32 v9, 0xbfb8aa3b, v35
	v_exp_f32_e32 v9, v9
	s_nop 0
	v_add_f32_e32 v1, 1.0, v9
	v_rcp_f32_e32 v9, v1
	s_nop 0
	v_mul_f32_e32 v35, v35, v9
	ds_write_b32 v7, v35 offset:51200
	s_waitcnt vmcnt(9)
	v_mul_f32_e32 v9, 0xbfb8aa3b, v36
	v_exp_f32_e32 v9, v9
	s_nop 0
	v_add_f32_e32 v1, 1.0, v9
	v_rcp_f32_e32 v9, v1
	s_nop 0
	v_mul_f32_e32 v36, v36, v9
	ds_write_b32 v7, v36 offset:53248
	s_waitcnt vmcnt(8)
	v_mul_f32_e32 v9, 0xbfb8aa3b, v37
	v_exp_f32_e32 v9, v9
	s_nop 0
	v_add_f32_e32 v1, 1.0, v9
	v_rcp_f32_e32 v9, v1
	s_nop 0
	v_mul_f32_e32 v37, v37, v9
	ds_write_b32 v7, v37 offset:55296
	s_waitcnt vmcnt(7)
	v_mul_f32_e32 v9, 0xbfb8aa3b, v38
	v_exp_f32_e32 v9, v9
	s_nop 0
	v_add_f32_e32 v1, 1.0, v9
	v_rcp_f32_e32 v9, v1
	s_nop 0
	v_mul_f32_e32 v38, v38, v9
	ds_write_b32 v7, v38 offset:57344
	s_waitcnt vmcnt(6)
	v_mul_f32_e32 v9, 0xbfb8aa3b, v39
	v_exp_f32_e32 v9, v9
	s_nop 0
	v_add_f32_e32 v1, 1.0, v9
	v_rcp_f32_e32 v9, v1
	s_nop 0
	v_mul_f32_e32 v39, v39, v9
	ds_write_b32 v7, v39 offset:59392
	s_waitcnt vmcnt(5)
	v_mul_f32_e32 v9, 0xbfb8aa3b, v40
	v_exp_f32_e32 v9, v9
	s_nop 0
	v_add_f32_e32 v1, 1.0, v9
	v_rcp_f32_e32 v9, v1
	s_nop 0
	v_mul_f32_e32 v40, v40, v9
	ds_write_b32 v7, v40 offset:61440
	s_waitcnt vmcnt(4)
	v_mul_f32_e32 v9, 0xbfb8aa3b, v41
	v_exp_f32_e32 v9, v9
	s_nop 0
	v_add_f32_e32 v1, 1.0, v9
	v_rcp_f32_e32 v9, v1
	s_nop 0
	v_mul_f32_e32 v41, v41, v9
	ds_write_b32 v7, v41 offset:63488
	v_add_u32_e32 v7, 0x10000, v7
	s_waitcnt vmcnt(3)
	v_mul_f32_e32 v9, 0xbfb8aa3b, v42
	v_exp_f32_e32 v9, v9
	s_nop 0
	v_add_f32_e32 v1, 1.0, v9
	v_rcp_f32_e32 v9, v1
	s_nop 0
	v_mul_f32_e32 v42, v42, v9
	ds_write_b32 v7, v42
	s_waitcnt vmcnt(2)
	v_mul_f32_e32 v9, 0xbfb8aa3b, v43
	v_exp_f32_e32 v9, v9
	s_nop 0
	v_add_f32_e32 v1, 1.0, v9
	v_rcp_f32_e32 v9, v1
	s_nop 0
	v_mul_f32_e32 v43, v43, v9
	ds_write_b32 v7, v43 offset:2048
	s_waitcnt vmcnt(1)
	v_mul_f32_e32 v9, 0xbfb8aa3b, v44
	v_exp_f32_e32 v9, v9
	s_nop 0
	v_add_f32_e32 v1, 1.0, v9
	v_rcp_f32_e32 v9, v1
	s_nop 0
	v_mul_f32_e32 v44, v44, v9
	ds_write_b32 v7, v44 offset:4096
	s_waitcnt vmcnt(0)
	v_mul_f32_e32 v9, 0xbfb8aa3b, v45
	v_exp_f32_e32 v9, v9
	s_nop 0
	v_add_f32_e32 v1, 1.0, v9
	v_rcp_f32_e32 v9, v1
	s_nop 0
	v_mul_f32_e32 v45, v45, v9
	ds_write_b32 v7, v45 offset:6144
	s_mov_b64 s[12:13], 0x800
	s_mov_b64 s[10:11], exec

; __device__ __forceinline__ unsigned pk2(float lo, float hi) { const f32x2 v = {lo, hi}; return __builtin_bit_cast(unsigned, __builtin_convertvector(v, bf2n_t_)); }
; __device__ __forceinline__ float fsigmoid(float x) { return __builtin_amdgcn_rcpf(1.0f + fexp(-x)); }
; __device__ __forceinline__ float ftanh(float x) { const float e = fexp(-2.0f * fabsf(x)); const float t = (1.0f - e) * __builtin_amdgcn_rcpf(1.0f + e); return x < 0.f ? -t : t; }
; __device__ __forceinline__ void phase_prep(const Frame& F, ArgsRef A, int l) {
;     ...
;         for (int m = gw; m < MT; m += NGW) {
;             int idx, len; if (m < ML) { idx = m & (SEQ - 1); len = SEQ; } else { idx = (m - ML) & (CL - 1); len = CL; }
;             const float fl = idx > 0 ? 1.f : 0.f, fr = idx < len - 1 ? 1.f : 0.f;
;             const bf16* z0 = ZR + (size_t)m * ZR_W; const bf16* zl = idx > 0 ? z0 - ZR_W : z0; const bf16* zrr = idx < len - 1 ? z0 + ZR_W : z0;
; #pragma unroll
;             for (int it = 0; it < 6; ++it) {
;                 unsigned o = 0u;
;                 if (scol[it] >= 0) {
;                     const unsigned wc = *(const unsigned*)(z0 + scol[it]), wl = *(const unsigned*)(zl + scol[it]), wr = *(const unsigned*)(zrr + scol[it]);
;                     float c0 = bflo(wc) * t1[it][0] + fl * bflo(wl) * t0[it][0] + fr * bflo(wr) * t2[it][0];
;                     float c1 = bfhi(wc) * t1[it][1] + fl * bfhi(wl) * t0[it][1] + fr * bfhi(wr) * t2[it][1];
;                     const int sec = it >> 1;
;                     if (sec == 0) { c0 = ftanh(c0); c1 = ftanh(c1); } else if (sec == 2) { c0 = fsigmoid(c0); c1 = fsigmoid(c1); }
;                     o = pk2(c0, c1);
;                 }
;                 *(unsigned*)(LA + (size_t)m * LA_W + 2 * (lane + 64 * it)) = o;
;             }
;         }
.LBB0_566:
	s_cmpk_lt_i32 s1, 0x4000
	s_cselect_b32 s31, 0x7ff, s37
	s_and_b32 s33, s31, s1
	s_cmp_eq_u32 s33, 0
	s_cselect_b64 s[26:27], -1, 0
	v_cndmask_b32_e64 v50, 1.0, 0, s[26:27]
	s_and_b64 s[26:27], s[26:27], exec
	s_cselect_b32 s15, 0, 0xffffe200
	s_cselect_b32 s19, 0, -1
	s_cmp_eq_u32 s33, s31
	s_cselect_b64 s[26:27], -1, 0
	v_cndmask_b32_e64 v51, 1.0, 0, s[26:27]
	s_and_b64 s[26:27], s[26:27], exec
	s_cselect_b32 s31, 0, 0x1e00
	v_mov_b32_e32 v61, 0
	v_mov_b32_e32 v62, 0
	s_mov_b64 s[26:27], exec
	s_and_b64 exec, s[26:27], s[2:3]
	s_add_u32 s34, s16, 0x15e00000
	s_addc_u32 s35, s17, 0
	v_lshl_add_u64 v[138:139], s[34:35], 0, v[38:39]
	global_load_dword v120, v[138:139], off
	s_add_u32 s34, s34, s15
	s_addc_u32 s35, s35, s19
	v_lshl_add_u64 v[138:139], s[34:35], 0, v[38:39]
	global_load_dword v121, v[138:139], off
	s_add_u32 s34, s16, 0x15e00000
	s_addc_u32 s35, s17, 0
	s_add_u32 s34, s34, s31
	s_addc_u32 s35, s35, 0
	v_lshl_add_u64 v[138:139], s[34:35], 0, v[38:39]
	global_load_dword v122, v[138:139], off
	s_and_b64 exec, s[26:27], s[4:5]
	v_lshl_add_u64 v[138:139], s[16:17], 0, v[40:41]
	global_load_dword v123, v[138:139], off
	s_add_u32 s34, s16, s15
	s_addc_u32 s35, s17, s19
	v_lshl_add_u64 v[138:139], s[34:35], 0, v[40:41]
	global_load_dword v124, v[138:139], off
	s_add_u32 s34, s16, s31
	s_addc_u32 s35, s17, 0
	v_lshl_add_u64 v[138:139], s[34:35], 0, v[40:41]
	global_load_dword v125, v[138:139], off
	s_and_b64 exec, s[26:27], s[6:7]
	v_lshl_add_u64 v[138:139], s[16:17], 0, v[42:43]
	global_load_dword v126, v[138:139], off
	s_add_u32 s34, s16, s15
	s_addc_u32 s35, s17, s19
	v_lshl_add_u64 v[138:139], s[34:35], 0, v[42:43]
	global_load_dword v127, v[138:139], off
	s_add_u32 s34, s16, s31
	s_addc_u32 s35, s17, 0
	v_lshl_add_u64 v[138:139], s[34:35], 0, v[42:43]
	global_load_dword v128, v[138:139], off
	s_and_b64 exec, s[26:27], s[8:9]
	v_lshl_add_u64 v[138:139], s[16:17], 0, v[44:45]
	global_load_dword v129, v[138:139], off
	s_add_u32 s34, s16, s15
	s_addc_u32 s35, s17, s19
	v_lshl_add_u64 v[138:139], s[34:35], 0, v[44:45]
	global_load_dword v130, v[138:139], off
	s_add_u32 s34, s16, s31
	s_addc_u32 s35, s17, 0
	v_lshl_add_u64 v[138:139], s[34:35], 0, v[44:45]
	global_load_dword v131, v[138:139], off
	s_and_b64 exec, s[26:27], s[10:11]
	v_lshl_add_u64 v[138:139], s[16:17], 0, v[46:47]
	global_load_dword v132, v[138:139], off
	s_add_u32 s34, s16, s15
	s_addc_u32 s35, s17, s19
	v_lshl_add_u64 v[138:139], s[34:35], 0, v[46:47]
	global_load_dword v133, v[138:139], off
	s_add_u32 s34, s16, s31
	s_addc_u32 s35, s17, 0
	v_lshl_add_u64 v[138:139], s[34:35], 0, v[46:47]
	global_load_dword v134, v[138:139], off
	s_and_b64 exec, s[26:27], s[12:13]
	v_lshl_add_u64 v[138:139], s[16:17], 0, v[48:49]
	global_load_dword v135, v[138:139], off
	s_add_u32 s34, s16, s15
	s_addc_u32 s35, s17, s19
	v_lshl_add_u64 v[138:139], s[34:35], 0, v[48:49]
	global_load_dword v136, v[138:139], off
	s_add_u32 s34, s16, s31
	s_addc_u32 s35, s17, 0
	v_lshl_add_u64 v[138:139], s[34:35], 0, v[48:49]
	global_load_dword v137, v[138:139], off
	s_mov_b64 exec, s[26:27]
	s_and_saveexec_b64 s[26:27], s[2:3]
	s_cbranch_execz .LBB0_568
	v_lshl_add_u64 v[52:53], s[16:17], 0, v[38:39]
	s_add_u32 s34, s16, s15
	v_add_co_u32_e32 v52, vcc, 0x15e00000, v52
	s_addc_u32 s35, s17, s19
	s_nop 0
	v_addc_co_u32_e32 v53, vcc, 0, v53, vcc
	v_lshl_add_u64 v[62:63], s[34:35], 0, v[38:39]
	s_mov_b32 s33, 0x15e00000
	s_add_u32 s34, s16, s31
	v_add_co_u32_e32 v62, vcc, s33, v62
	s_addc_u32 s35, s17, 0
	s_nop 0
	v_addc_co_u32_e32 v63, vcc, 0, v63, vcc
	s_nop 0
	s_nop 0
	s_nop 0
	v_lshl_add_u64 v[52:53], s[34:35], 0, v[38:39]
	v_add_co_u32_e32 v52, vcc, s33, v52
	s_waitcnt vmcnt(15)
	v_and_b32_e32 v63, 0xffff0000, v121
	v_addc_co_u32_e32 v53, vcc, 0, v53, vcc
	s_nop 0
	v_lshlrev_b32_e32 v62, 16, v121
	v_pk_mul_f32 v[62:63], v[50:51], v[62:63] op_sel_hi:[0,1]
	v_and_b32_e32 v53, 0xffff0000, v120
	v_lshlrev_b32_e32 v52, 16, v120
	v_pk_mul_f32 v[62:63], v[6:7], v[62:63]
	s_waitcnt vmcnt(15)
	v_and_b32_e32 v65, 0xffff0000, v122
	v_lshlrev_b32_e32 v64, 16, v122
	v_pk_fma_f32 v[52:53], v[4:5], v[52:53], v[62:63]
	v_pk_mul_f32 v[62:63], v[50:51], v[64:65] op_sel:[1,0]
	s_nop 0
	v_pk_fma_f32 v[52:53], v[8:9], v[62:63], v[52:53]
	s_nop 0
	v_mul_f32_e64 v62, |v53|, -2.0
	v_mul_f32_e64 v63, |v52|, -2.0
	v_mul_f32_e32 v62, 0x3fb8aa3b, v62
	v_mul_f32_e32 v64, 0x3fb8aa3b, v63
	v_exp_f32_e32 v63, v62
	v_exp_f32_e32 v62, v64
	v_cmp_gt_f32_e32 vcc, 0, v53
	v_add_f32_e32 v64, 1.0, v63
	v_add_f32_e32 v66, 1.0, v62
	v_rcp_f32_e32 v65, v64
	v_rcp_f32_e32 v64, v66
	v_pk_add_f32 v[62:63], v[62:63], 1.0 op_sel_hi:[1,0] neg_lo:[1,0] neg_hi:[1,0]
	s_nop 0
	v_pk_mul_f32 v[62:63], v[62:63], v[64:65]
	s_nop 0
	v_cndmask_b32_e64 v53, v63, -v63, vcc
	v_cmp_gt_f32_e32 vcc, 0, v52
	s_nop 1
	v_cndmask_b32_e64 v52, v62, -v62, vcc
	v_cvt_pk_bf16_f32 v62, v52, v53
; __device__ __forceinline__ unsigned pk2(float lo, float hi) { const f32x2 v = {lo, hi}; return __builtin_bit_cast(unsigned, __builtin_convertvector(v, bf2n_t_)); }
; __device__ __forceinline__ float fsigmoid(float x) { return __builtin_amdgcn_rcpf(1.0f + fexp(-x)); }
; __device__ __forceinline__ float ftanh(float x) { const float e = fexp(-2.0f * fabsf(x)); const float t = (1.0f - e) * __builtin_amdgcn_rcpf(1.0f + e); return x < 0.f ? -t : t; }
; __device__ __forceinline__ void phase_prep(const Frame& F, ArgsRef A, int l) {
;     ...
;         for (int m = gw; m < MT; m += NGW) {
;             int idx, len; if (m < ML) { idx = m & (SEQ - 1); len = SEQ; } else { idx = (m - ML) & (CL - 1); len = CL; }
;             const float fl = idx > 0 ? 1.f : 0.f, fr = idx < len - 1 ? 1.f : 0.f;
;             const bf16* z0 = ZR + (size_t)m * ZR_W; const bf16* zl = idx > 0 ? z0 - ZR_W : z0; const bf16* zrr = idx < len - 1 ? z0 + ZR_W : z0;
; #pragma unroll
;             for (int it = 0; it < 6; ++it) {
;                 unsigned o = 0u;
;                 if (scol[it] >= 0) {
;                     const unsigned wc = *(const unsigned*)(z0 + scol[it]), wl = *(const unsigned*)(zl + scol[it]), wr = *(const unsigned*)(zrr + scol[it]);
;                     float c0 = bflo(wc) * t1[it][0] + fl * bflo(wl) * t0[it][0] + fr * bflo(wr) * t2[it][0];
;                     float c1 = bfhi(wc) * t1[it][1] + fl * bfhi(wl) * t0[it][1] + fr * bfhi(wr) * t2[it][1];
;                     const int sec = it >> 1;
;                     if (sec == 0) { c0 = ftanh(c0); c1 = ftanh(c1); } else if (sec == 2) { c0 = fsigmoid(c0); c1 = fsigmoid(c1); }
;                     o = pk2(c0, c1);
;                 }
;                 *(unsigned*)(LA + (size_t)m * LA_W + 2 * (lane + 64 * it)) = o;
;             }
;         }
.LBB0_568:
	s_or_b64 exec, exec, s[26:27]
	v_lshl_add_u64 v[52:53], s[16:17], 0, v[36:37]
	v_add_co_u32_e32 v64, vcc, 0x47100000, v52
	s_nop 1
	v_addc_co_u32_e32 v65, vcc, 0, v53, vcc
	global_store_dword v[64:65], v62, off
	v_mov_b32_e32 v62, 0
	s_and_saveexec_b64 s[26:27], s[4:5]
	s_cbranch_execz .LBB0_570
	s_add_u32 s34, s16, s15
	s_addc_u32 s35, s17, s19
	v_lshl_add_u64 v[62:63], s[16:17], 0, v[40:41]
	v_lshl_add_u64 v[64:65], s[34:35], 0, v[40:41]
	s_add_u32 s34, s16, s31
	s_nop 0
	s_nop 0
	s_nop 0
	s_addc_u32 s35, s17, 0
	v_lshl_add_u64 v[62:63], s[34:35], 0, v[40:41]
	s_nop 0
	s_waitcnt vmcnt(13)
	v_and_b32_e32 v63, 0xffff0000, v123
	v_and_b32_e32 v65, 0xffff0000, v124
	v_lshlrev_b32_e32 v64, 16, v124
	v_pk_mul_f32 v[64:65], v[50:51], v[64:65] op_sel_hi:[0,1]
	v_lshlrev_b32_e32 v62, 16, v123
	v_and_b32_e32 v67, 0xffff0000, v125
	v_lshlrev_b32_e32 v66, 16, v125
	v_pk_mul_f32 v[64:65], v[12:13], v[64:65]
	s_nop 0
	v_pk_fma_f32 v[62:63], v[10:11], v[62:63], v[64:65]
	v_pk_mul_f32 v[64:65], v[50:51], v[66:67] op_sel:[1,0]
	s_nop 0
	v_pk_fma_f32 v[62:63], v[14:15], v[64:65], v[62:63]
	s_nop 0
	v_mul_f32_e64 v64, |v63|, -2.0
	v_mul_f32_e64 v65, |v62|, -2.0
	v_mul_f32_e32 v64, 0x3fb8aa3b, v64
	v_mul_f32_e32 v66, 0x3fb8aa3b, v65
	v_exp_f32_e32 v65, v64
	v_exp_f32_e32 v64, v66
	v_cmp_gt_f32_e32 vcc, 0, v63
	v_add_f32_e32 v66, 1.0, v65
	v_add_f32_e32 v68, 1.0, v64
	v_rcp_f32_e32 v67, v66
	v_rcp_f32_e32 v66, v68
	v_pk_add_f32 v[64:65], v[64:65], 1.0 op_sel_hi:[1,0] neg_lo:[1,0] neg_hi:[1,0]
	s_nop 0
	v_pk_mul_f32 v[64:65], v[64:65], v[66:67]
	s_nop 0
	v_cndmask_b32_e64 v63, v65, -v65, vcc
	v_cmp_gt_f32_e32 vcc, 0, v62
	s_nop 1
	v_cndmask_b32_e64 v62, v64, -v64, vcc
	v_cvt_pk_bf16_f32 v62, v62, v63
.LBB0_570:
	s_or_b64 exec, exec, s[26:27]
	v_add_co_u32_e32 v64, vcc, 0x47100000, v52
	s_nop 1
	v_addc_co_u32_e32 v65, vcc, 0, v53, vcc
	global_store_dword v[64:65], v62, off offset:256
	s_and_saveexec_b64 s[26:27], s[6:7]
	s_cbranch_execz .LBB0_572
	s_add_u32 s34, s16, s15
	s_addc_u32 s35, s17, s19
	v_lshl_add_u64 v[62:63], s[16:17], 0, v[42:43]
	v_lshl_add_u64 v[64:65], s[34:35], 0, v[42:43]
	s_add_u32 s34, s16, s31
	s_nop 0
	s_nop 0
	s_nop 0
	s_addc_u32 s35, s17, 0
	v_lshl_add_u64 v[62:63], s[34:35], 0, v[42:43]
	s_nop 0
	s_waitcnt vmcnt(11)
	v_lshlrev_b32_e32 v62, 16, v126
	v_lshlrev_b32_e32 v64, 16, v127
	v_and_b32_e32 v65, 0xffff0000, v127
	v_pk_mul_f32 v[64:65], v[50:51], v[64:65] op_sel_hi:[0,1]
	v_and_b32_e32 v63, 0xffff0000, v126
	v_lshlrev_b32_e32 v66, 16, v128
	v_and_b32_e32 v67, 0xffff0000, v128
	v_pk_mul_f32 v[64:65], v[18:19], v[64:65]
	s_nop 0
	v_pk_fma_f32 v[62:63], v[16:17], v[62:63], v[64:65]
	v_pk_mul_f32 v[64:65], v[50:51], v[66:67] op_sel:[1,0]
	s_nop 0
	v_pk_fma_f32 v[62:63], v[20:21], v[64:65], v[62:63]
	s_nop 0
	v_cvt_pk_bf16_f32 v61, v62, v63
.LBB0_572:
	s_or_b64 exec, exec, s[26:27]
	v_add_co_u32_e32 v62, vcc, 0x47100000, v52
	s_nop 1
	v_addc_co_u32_e32 v63, vcc, 0, v53, vcc
	global_store_dword v[62:63], v61, off offset:512
	v_mov_b32_e32 v61, 0
	v_mov_b32_e32 v62, 0
	s_and_saveexec_b64 s[26:27], s[8:9]
	s_cbranch_execz .LBB0_574
	s_add_u32 s34, s16, s15
	s_addc_u32 s35, s17, s19
	v_lshl_add_u64 v[62:63], s[16:17], 0, v[44:45]
	v_lshl_add_u64 v[64:65], s[34:35], 0, v[44:45]
	s_add_u32 s34, s16, s31
	s_nop 0
	s_nop 0
	s_nop 0
	s_addc_u32 s35, s17, 0
	v_lshl_add_u64 v[62:63], s[34:35], 0, v[44:45]
	s_nop 0
	s_waitcnt vmcnt(9)
	v_lshlrev_b32_e32 v62, 16, v129
	v_lshlrev_b32_e32 v64, 16, v130
	v_and_b32_e32 v65, 0xffff0000, v130
	v_pk_mul_f32 v[64:65], v[50:51], v[64:65] op_sel_hi:[0,1]
	v_and_b32_e32 v63, 0xffff0000, v129
	v_lshlrev_b32_e32 v66, 16, v131
	v_and_b32_e32 v67, 0xffff0000, v131
	v_pk_mul_f32 v[64:65], v[24:25], v[64:65]
	s_nop 0
	v_pk_fma_f32 v[62:63], v[22:23], v[62:63], v[64:65]
	v_pk_mul_f32 v[64:65], v[50:51], v[66:67] op_sel:[1,0]
	s_nop 0
	v_pk_fma_f32 v[62:63], v[26:27], v[64:65], v[62:63]
	s_nop 0
	v_cvt_pk_bf16_f32 v62, v62, v63
.LBB0_574:
	s_or_b64 exec, exec, s[26:27]
	v_add_co_u32_e32 v64, vcc, 0x47100000, v52
	s_nop 1
	v_addc_co_u32_e32 v65, vcc, 0, v53, vcc
	global_store_dword v[64:65], v62, off offset:768
	s_and_saveexec_b64 s[26:27], s[10:11]
	s_cbranch_execz .LBB0_576
	s_add_u32 s34, s16, s15
	v_lshl_add_u64 v[62:63], s[16:17], 0, v[46:47]
	s_addc_u32 s35, s17, s19
	s_nop 0
	v_lshl_add_u64 v[62:63], s[34:35], 0, v[46:47]
	s_add_u32 s34, s16, s31
	s_addc_u32 s35, s17, 0
	s_nop 0
	v_lshl_add_u64 v[62:63], s[34:35], 0, v[46:47]
	s_nop 0
	s_waitcnt vmcnt(7)
	v_lshlrev_b32_e32 v66, 16, v132
	v_and_b32_e32 v61, 0xffff0000, v132
	v_lshlrev_b32_e32 v62, 16, v133
	v_lshlrev_b32_e32 v63, 16, v134
	v_pk_mul_f32 v[62:63], v[50:51], v[62:63]
	s_nop 0
	v_pk_mul_f32 v[62:63], v[28:29], v[62:63]
	s_nop 0
	v_fma_f32 v62, v58, v66, v62
	v_add_f32_e32 v66, v62, v63
	v_and_b32_e32 v63, 0xffff0000, v134
	v_and_b32_e32 v62, 0xffff0000, v133
	v_pk_mul_f32 v[62:63], v[50:51], v[62:63]
	s_nop 0
	v_pk_mul_f32 v[62:63], v[30:31], v[62:63]
	s_nop 0
	v_fma_f32 v61, v57, v61, v62
	v_add_f32_e32 v61, v61, v63
	v_mul_f32_e32 v61, 0xbfb8aa3b, v61
	v_mul_f32_e32 v62, 0xbfb8aa3b, v66
	v_exp_f32_e32 v61, v61
	v_exp_f32_e32 v62, v62
	v_add_f32_e32 v61, 1.0, v61
	v_add_f32_e32 v62, 1.0, v62
	v_rcp_f32_e32 v61, v61
	v_rcp_f32_e32 v62, v62
	s_nop 0
	v_cvt_pk_bf16_f32 v61, v62, v61
.LBB0_576:
	s_or_b64 exec, exec, s[26:27]
	v_add_co_u32_e32 v62, vcc, 0x47100000, v52
	s_nop 1
	v_addc_co_u32_e32 v63, vcc, 0, v53, vcc
	global_store_dword v[62:63], v61, off offset:1024
	v_mov_b32_e32 v61, 0
	s_and_saveexec_b64 s[26:27], s[12:13]
	s_cbranch_execz .LBB0_565
	s_add_u32 s34, s16, s15
	v_lshl_add_u64 v[62:63], s[16:17], 0, v[48:49]
	s_addc_u32 s35, s17, s19
	s_nop 0
	v_lshl_add_u64 v[62:63], s[34:35], 0, v[48:49]
	s_add_u32 s34, s16, s31
	s_addc_u32 s35, s17, 0
	s_nop 0
	v_lshl_add_u64 v[62:63], s[34:35], 0, v[48:49]
	s_nop 0
	s_waitcnt vmcnt(5)
	v_lshlrev_b32_e32 v66, 16, v135
	v_and_b32_e32 v61, 0xffff0000, v135
	v_lshlrev_b32_e32 v62, 16, v136
	v_lshlrev_b32_e32 v63, 16, v137
	v_pk_mul_f32 v[62:63], v[50:51], v[62:63]
	s_nop 0
	v_pk_mul_f32 v[62:63], v[32:33], v[62:63]
	s_nop 0
	v_fma_f32 v62, v60, v66, v62
	v_add_f32_e32 v66, v62, v63
	v_and_b32_e32 v63, 0xffff0000, v137
	v_and_b32_e32 v62, 0xffff0000, v136
	v_pk_mul_f32 v[50:51], v[50:51], v[62:63]
	s_nop 0
	v_pk_mul_f32 v[50:51], v[34:35], v[50:51]
	s_nop 0
	v_fma_f32 v50, v59, v61, v50
	v_add_f32_e32 v50, v50, v51
	v_mul_f32_e32 v50, 0xbfb8aa3b, v50
	v_mul_f32_e32 v51, 0xbfb8aa3b, v66
	v_exp_f32_e32 v50, v50
	v_exp_f32_e32 v51, v51
	v_add_f32_e32 v50, 1.0, v50
	v_add_f32_e32 v51, 1.0, v51
	v_rcp_f32_e32 v50, v50
	v_rcp_f32_e32 v51, v51
	s_nop 0
	v_cvt_pk_bf16_f32 v61, v51, v50
	s_branch .LBB0_565
